# big-GEMM tile setup: wait for stage 0 (vmcnt(6)+barrier) moved behind the pointer math and accumulator clears
# speedup vs baseline: 1.0053x; 1.0053x over previous
; DI int otid() { int t = threadIdx.x; asm volatile("" : "+v"(t)); return t; }
;   DI bf16* K() const { return (bf16*)(p.ws + WS_K); }
; template <class AP, class BP, class Epi>
; DI void mfma_gemm_big_tile(const AP& aptr, const BP& bptr, int m0, int n0, int K, const Epi& epi, bf16* lds) {
;   const int tid = otid(), lane = tid & 63, wave = __builtin_amdgcn_readfirstlane(tid >> 6);
;   const int wm = (wave >> 1) * 128, wn = (wave & 1) * 64;
;   const int l16 = lane & 15, lq = lane >> 4;
;   const int lrow = tid >> 2, lcol = ((tid & 3) ^ ((-(tid >> 4)) & 3)) * 8;
;   const bf16* ap[4]; const bf16* bp[2];
; #pragma unroll
;   for (int i = 0; i < 4; ++i) ap[i] = aptr(m0 + lrow + 64 * i) + lcol;
; #pragma unroll
;   for (int i = 0; i < 2; ++i) bp[i] = bptr(n0 + lrow + 64 * i) + lcol;
;   f32x4 acc[8][4];
; #pragma unroll
;   for (int i = 0; i < 8; ++i)
; #pragma unroll
;     for (int j = 0; j < 4; ++j) acc[i][j] = f32x4{0.f, 0.f, 0.f, 0.f};
;   const int nk = K >> 5;
;     ...
;   BG_ISSUE(0, 0);
;   BG_ISSUE(1, 1);
;   asm volatile("s_waitcnt vmcnt(6)\n\ts_barrier" ::: "memory");
;   const unsigned lbase = (unsigned)(size_t)lds;
;   const unsigned a_off = (unsigned)(((wm + l16) * 32 + (lq ^ ((-(l16 >> 2)) & 3)) * 8) * 2);
;   const unsigned b_off = (unsigned)((256 * 32 + (wn + l16) * 32 + (lq ^ ((-(l16 >> 2)) & 3)) * 8) * 2);
.LBB0_248:
	s_mul_i32 s0, s8, s2
	s_add_i32 s0, s9, s0
	s_mul_hi_i32 s1, s0, 0x66666667
	s_lshr_b32 s4, s1, 31
	s_ashr_i32 s1, s1, 3
	v_mov_b32_e32 v26, v172
	s_add_i32 s1, s1, s4
	s_lshl_b32 s10, s1, 8
	v_lshrrev_b32_e32 v142, 4, v26
	s_mul_i32 s1, s1, 20
	v_sub_u32_e32 v27, 0, v142
	s_sub_i32 s0, s0, s1
	v_ashrrev_i32_e32 v18, 2, v26
	v_xor_b32_e32 v0, v26, v27
	s_lshl_b32 s11, s0, 7
	v_readfirstlane_b32 s0, v26
	v_add_u32_e32 v2, s10, v18
	v_lshlrev_b32_e32 v0, 4, v0
	s_and_b32 s12, s0, 64
	v_and_b32_e32 v0, 48, v0
	v_ashrrev_i32_e32 v3, 31, v2
	v_add_u32_e32 v10, 64, v2
	s_and_b32 s17, s0, 0xffffff80
	s_lshl_b32 s0, s0, 4
	v_lshl_add_u64 v[4:5], s[60:61], 0, v[0:1]
	v_bfe_u32 v30, v26, 2, 1
	v_mul_i32_i24_e32 v30, 0xfffff840, v30
	v_ashrrev_i32_e32 v31, 31, v30
	v_lshl_add_u64 v[4:5], v[4:5], 0, v[30:31]
	v_lshlrev_b64 v[6:7], 11, v[2:3]
	v_ashrrev_i32_e32 v11, 31, v10
	v_add_u32_e32 v14, 0x80, v2
	s_and_b32 s18, s0, 0xfffffc00
	v_lshl_add_u64 v[8:9], v[4:5], 0, v[6:7]
	v_lshlrev_b64 v[10:11], 11, v[10:11]
	v_ashrrev_i32_e32 v15, 31, v14
	v_add_u32_e32 v2, 0xc0, v2
	v_add_u32_e32 v18, s11, v18
	s_mov_b32 m0, s18
	v_lshl_add_u64 v[12:13], v[4:5], 0, v[10:11]
	v_lshlrev_b64 v[14:15], 11, v[14:15]
	v_ashrrev_i32_e32 v3, 31, v2
	v_ashrrev_i32_e32 v19, 31, v18
	global_load_lds_dwordx4 v[8:9], off
	s_add_i32 m0, s18, 0x1000
	v_lshl_add_u64 v[16:17], v[4:5], 0, v[14:15]
	v_lshlrev_b64 v[2:3], 11, v[2:3]
	v_lshlrev_b64 v[22:23], 11, v[18:19]
	v_add_u32_e32 v18, 64, v18
	global_load_lds_dwordx4 v[12:13], off
	s_add_i32 m0, s18, 0x2000
	v_lshl_add_u64 v[4:5], v[4:5], 0, v[2:3]
	v_lshl_add_u64 v[20:21], s[52:53], 0, v[0:1]
	v_lshl_add_u64 v[20:21], v[20:21], 0, v[30:31]
	v_ashrrev_i32_e32 v19, 31, v18
	global_load_lds_dwordx4 v[16:17], off
	s_add_i32 m0, s18, 0x3000
	v_lshl_add_u64 v[24:25], v[20:21], 0, v[22:23]
	v_lshlrev_b64 v[18:19], 11, v[18:19]
	global_load_lds_dwordx4 v[4:5], off
	s_add_i32 m0, s18, 0x4000
	v_lshl_add_u64 v[20:21], v[20:21], 0, v[18:19]
	global_load_lds_dwordx4 v[24:25], off
	s_add_i32 m0, s18, 0x5000
	v_lshl_add_u64 v[8:9], v[8:9], 0, 64
	v_lshl_add_u64 v[8:9], v[8:9], 0, 64
	global_load_lds_dwordx4 v[20:21], off
	s_add_i32 m0, s18, 0x6000
	v_lshl_add_u64 v[4:5], v[4:5], 0, 64
	v_lshl_add_u64 v[4:5], v[4:5], 0, 64
	global_load_lds_dwordx4 v[8:9], off
	v_lshl_add_u64 v[8:9], v[12:13], 0, 64
	v_lshl_add_u64 v[8:9], v[8:9], 0, 64
	s_add_i32 m0, s18, 0x7000
	v_and_b32_e32 v0, 15, v26
	global_load_lds_dwordx4 v[8:9], off
	v_lshl_add_u64 v[8:9], v[16:17], 0, 64
	v_lshl_add_u64 v[8:9], v[8:9], 0, 64
	s_add_i32 m0, s18, 0x8000
	v_readlane_b32 s0, v253, 53
	global_load_lds_dwordx4 v[8:9], off
	s_add_i32 m0, s18, 0x9000
	v_readlane_b32 s1, v253, 54
	global_load_lds_dwordx4 v[4:5], off
	v_lshl_add_u64 v[4:5], v[24:25], 0, 64
	v_lshl_add_u64 v[4:5], v[4:5], 0, 64
	s_add_i32 m0, s18, 0xa000
	s_mov_b32 s13, 2
	global_load_lds_dwordx4 v[4:5], off
	v_lshl_add_u64 v[4:5], v[20:21], 0, 64
	v_lshl_add_u64 v[4:5], v[4:5], 0, 64
	s_add_i32 m0, s18, 0xb000
	s_mov_b32 s16, 0
	global_load_lds_dwordx4 v[4:5], off
	v_lshrrev_b32_e32 v5, 2, v26
	v_sub_u32_e32 v5, 0, v5
	v_xor_b32_e32 v5, v142, v5
	v_lshlrev_b32_e32 v5, 4, v5
	v_or_b32_e32 v4, s17, v0
	v_and_b32_e32 v5, 48, v5
	v_lshl_or_b32 v143, v4, 6, v5
	v_or_b32_e32 v4, s12, v0
	v_lshlrev_b32_e32 v4, 6, v4
	v_or3_b32 v144, v5, v4, s77
	v_bitop3_b32 v4, v26, 3, v27 bitop3:0x48
	v_lshlrev_b32_e32 v4, 4, v4
	v_or_b32_e32 v18, v18, v4
	v_or_b32_e32 v22, v22, v4
	v_lshl_add_u64 v[130:131], s[0:1], 0, v[18:19]
	v_lshl_add_u64 v[132:133], s[0:1], 0, v[22:23]
	v_readlane_b32 s0, v253, 55
	v_or_b32_e32 v2, v2, v4
	v_readlane_b32 s1, v253, 56
	v_or_b32_e32 v14, v14, v4
;   DI bf16* K() const { return (bf16*)(p.ws + WS_K); }
; template <class AP, class BP, class Epi>
; DI void mfma_gemm_big_tile(const AP& aptr, const BP& bptr, int m0, int n0, int K, const Epi& epi, bf16* lds) {
;     ...
;   const bf16* ap[4]; const bf16* bp[2];
; #pragma unroll
;   for (int i = 0; i < 4; ++i) ap[i] = aptr(m0 + lrow + 64 * i) + lcol;
; #pragma unroll
;   for (int i = 0; i < 2; ++i) bp[i] = bptr(n0 + lrow + 64 * i) + lcol;
;   f32x4 acc[8][4];
; #pragma unroll
;   for (int i = 0; i < 8; ++i)
; #pragma unroll
;     for (int j = 0; j < 4; ++j) acc[i][j] = f32x4{0.f, 0.f, 0.f, 0.f};
;   const int nk = K >> 5;
;     ...
;   BG_ISSUE(0, 0);
;   BG_ISSUE(1, 1);
;   asm volatile("s_waitcnt vmcnt(6)\n\ts_barrier" ::: "memory");
	v_or_b32_e32 v10, v10, v4
	v_lshl_add_u64 v[134:135], s[0:1], 0, v[2:3]
	v_or_b32_e32 v6, v6, v4
	v_mov_b32_e32 v2, 0
	v_lshl_add_u64 v[136:137], s[0:1], 0, v[14:15]
	v_lshl_add_u64 v[138:139], s[0:1], 0, v[10:11]
	v_lshl_add_u64 v[140:141], s[0:1], 0, v[6:7]
	v_lshl_add_u64 v[30:31], v[30:31], 0, 64
	v_lshl_add_u64 v[30:31], v[30:31], 0, 64
	v_lshl_add_u64 v[130:131], v[130:131], 0, v[30:31]
	v_lshl_add_u64 v[132:133], v[132:133], 0, v[30:31]
	v_lshl_add_u64 v[134:135], v[134:135], 0, v[30:31]
	v_lshl_add_u64 v[136:137], v[136:137], 0, v[30:31]
	v_lshl_add_u64 v[138:139], v[138:139], 0, v[30:31]
	v_lshl_add_u64 v[140:141], v[140:141], 0, v[30:31]
	s_mov_b64 s[0:1], 0
	s_mov_b32 s19, 0
	v_mov_b32_e32 v3, v2
	v_mov_b32_e32 v4, v2
	v_mov_b32_e32 v5, v2
	v_mov_b32_e32 v6, v2
	v_mov_b32_e32 v7, v2
	v_mov_b32_e32 v8, v2
	v_mov_b32_e32 v9, v2
	v_mov_b32_e32 v10, v2
	v_mov_b32_e32 v11, v2
	v_mov_b32_e32 v12, v2
	v_mov_b32_e32 v13, v2
	v_mov_b32_e32 v14, v2
	v_mov_b32_e32 v15, v2
	v_mov_b32_e32 v16, v2
	v_mov_b32_e32 v17, v2
	v_mov_b32_e32 v18, v2
	v_mov_b32_e32 v19, v2
	v_mov_b32_e32 v20, v2
	v_mov_b32_e32 v21, v2
	v_mov_b32_e32 v22, v2
	v_mov_b32_e32 v23, v2
	v_mov_b32_e32 v24, v2
	v_mov_b32_e32 v25, v2
	v_mov_b32_e32 v26, v2
	v_mov_b32_e32 v27, v2
	v_mov_b32_e32 v28, v2
	v_mov_b32_e32 v29, v2
	v_mov_b32_e32 v30, v2
	v_mov_b32_e32 v31, v2
	v_mov_b32_e32 v32, v2
	v_mov_b32_e32 v33, v2
	v_mov_b32_e32 v34, v2
	v_mov_b32_e32 v35, v2
	v_mov_b32_e32 v36, v2
	v_mov_b32_e32 v37, v2
	v_mov_b32_e32 v38, v2
	v_mov_b32_e32 v39, v2
	v_mov_b32_e32 v40, v2
	v_mov_b32_e32 v41, v2
	v_mov_b32_e32 v42, v2
	v_mov_b32_e32 v43, v2
	v_mov_b32_e32 v44, v2
	v_mov_b32_e32 v45, v2
	v_mov_b32_e32 v46, v2
	v_mov_b32_e32 v47, v2
	v_mov_b32_e32 v48, v2
	v_mov_b32_e32 v49, v2
	v_mov_b32_e32 v50, v2
	v_mov_b32_e32 v51, v2
	v_mov_b32_e32 v52, v2
	v_mov_b32_e32 v53, v2
	v_mov_b32_e32 v54, v2
	v_mov_b32_e32 v55, v2
	v_mov_b32_e32 v56, v2
	v_mov_b32_e32 v57, v2
	v_mov_b32_e32 v58, v2
	v_mov_b32_e32 v59, v2
	v_mov_b32_e32 v60, v2
	v_mov_b32_e32 v61, v2
	v_mov_b32_e32 v62, v2
	v_mov_b32_e32 v63, v2
	v_mov_b32_e32 v64, v2
	v_mov_b32_e32 v65, v2
	v_mov_b32_e32 v66, v2
	v_mov_b32_e32 v67, v2
	v_mov_b32_e32 v68, v2
	v_mov_b32_e32 v69, v2
	v_mov_b32_e32 v70, v2
	v_mov_b32_e32 v71, v2
	v_mov_b32_e32 v72, v2
	v_mov_b32_e32 v73, v2
	v_mov_b32_e32 v74, v2
	v_mov_b32_e32 v75, v2
	v_mov_b32_e32 v76, v2
	v_mov_b32_e32 v77, v2
	v_mov_b32_e32 v78, v2
	v_mov_b32_e32 v79, v2
	v_mov_b32_e32 v80, v2
	v_mov_b32_e32 v81, v2
	v_mov_b32_e32 v82, v2
	v_mov_b32_e32 v83, v2
	v_mov_b32_e32 v84, v2
	v_mov_b32_e32 v85, v2
	v_mov_b32_e32 v86, v2
	v_mov_b32_e32 v87, v2
	v_mov_b32_e32 v88, v2
	v_mov_b32_e32 v89, v2
	v_mov_b32_e32 v90, v2
	v_mov_b32_e32 v91, v2
	v_mov_b32_e32 v92, v2
	v_mov_b32_e32 v93, v2
	v_mov_b32_e32 v94, v2
	v_mov_b32_e32 v95, v2
	v_mov_b32_e32 v96, v2
	v_mov_b32_e32 v97, v2
	v_mov_b32_e32 v98, v2
	v_mov_b32_e32 v99, v2
	v_mov_b32_e32 v100, v2
	v_mov_b32_e32 v101, v2
	v_mov_b32_e32 v102, v2
	v_mov_b32_e32 v103, v2
	v_mov_b32_e32 v104, v2
	v_mov_b32_e32 v105, v2
	v_mov_b32_e32 v106, v2
	v_mov_b32_e32 v107, v2
	v_mov_b32_e32 v108, v2
	v_mov_b32_e32 v109, v2
	v_mov_b32_e32 v110, v2
	v_mov_b32_e32 v111, v2
	v_mov_b32_e32 v112, v2
	v_mov_b32_e32 v113, v2
	v_mov_b32_e32 v114, v2
	v_mov_b32_e32 v115, v2
	v_mov_b32_e32 v116, v2
	v_mov_b32_e32 v117, v2
	v_mov_b32_e32 v118, v2
	v_mov_b32_e32 v119, v2
	v_mov_b32_e32 v120, v2
	v_mov_b32_e32 v121, v2
	v_mov_b32_e32 v122, v2
	v_mov_b32_e32 v123, v2
	v_mov_b32_e32 v124, v2
	v_mov_b32_e32 v125, v2
	v_mov_b32_e32 v126, v2
	v_mov_b32_e32 v127, v2
	v_mov_b32_e32 v128, v2
	v_mov_b32_e32 v129, v2
	s_waitcnt vmcnt(6)
	s_barrier
	s_branch .LBB0_250

; DI int otid() { int t = threadIdx.x; asm volatile("" : "+v"(t)); return t; }
;   DI bf16* K() const { return (bf16*)(p.ws + WS_K); }
; template <class AP, class BP, class Epi>
; DI void mfma_gemm_big_tile(const AP& aptr, const BP& bptr, int m0, int n0, int K, const Epi& epi, bf16* lds) {
;   const int tid = otid(), lane = tid & 63, wave = __builtin_amdgcn_readfirstlane(tid >> 6);
;   const int wm = (wave >> 1) * 128, wn = (wave & 1) * 64;
;   const int l16 = lane & 15, lq = lane >> 4;
;   const int lrow = tid >> 2, lcol = ((tid & 3) ^ ((-(tid >> 4)) & 3)) * 8;
;   const bf16* ap[4]; const bf16* bp[2];
; #pragma unroll
;   for (int i = 0; i < 4; ++i) ap[i] = aptr(m0 + lrow + 64 * i) + lcol;
; #pragma unroll
;   for (int i = 0; i < 2; ++i) bp[i] = bptr(n0 + lrow + 64 * i) + lcol;
;   f32x4 acc[8][4];
; #pragma unroll
;   for (int i = 0; i < 8; ++i)
; #pragma unroll
;     for (int j = 0; j < 4; ++j) acc[i][j] = f32x4{0.f, 0.f, 0.f, 0.f};
;   const int nk = K >> 5;
;     ...
;   BG_ISSUE(0, 0);
;   BG_ISSUE(1, 1);
;   asm volatile("s_waitcnt vmcnt(6)\n\ts_barrier" ::: "memory");
;   const unsigned lbase = (unsigned)(size_t)lds;
;   const unsigned a_off = (unsigned)(((wm + l16) * 32 + (lq ^ ((-(l16 >> 2)) & 3)) * 8) * 2);
;   const unsigned b_off = (unsigned)((256 * 32 + (wn + l16) * 32 + (lq ^ ((-(l16 >> 2)) & 3)) * 8) * 2);
.LBB0_508:
	s_mul_i32 s0, s8, s2
	s_add_i32 s0, s9, s0
	s_mul_hi_i32 s1, s0, 0x66666667
	s_lshr_b32 s4, s1, 31
	s_ashr_i32 s1, s1, 3
	v_mov_b32_e32 v26, v172
	s_add_i32 s1, s1, s4
	s_lshl_b32 s10, s1, 8
	v_lshrrev_b32_e32 v142, 4, v26
	s_mul_i32 s1, s1, 20
	v_sub_u32_e32 v27, 0, v142
	s_sub_i32 s0, s0, s1
	v_ashrrev_i32_e32 v18, 2, v26
	v_xor_b32_e32 v0, v26, v27
	s_lshl_b32 s11, s0, 7
	v_readfirstlane_b32 s0, v26
	v_add_u32_e32 v2, s10, v18
	v_lshlrev_b32_e32 v0, 4, v0
	s_and_b32 s12, s0, 64
	v_and_b32_e32 v0, 48, v0
	v_ashrrev_i32_e32 v3, 31, v2
	v_add_u32_e32 v10, 64, v2
	s_and_b32 s16, s0, 0xffffff80
	s_lshl_b32 s0, s0, 4
	v_lshl_add_u64 v[4:5], s[60:61], 0, v[0:1]
	v_bfe_u32 v30, v26, 2, 1
	v_mul_i32_i24_e32 v30, 0xfffff840, v30
	v_ashrrev_i32_e32 v31, 31, v30
	v_lshl_add_u64 v[4:5], v[4:5], 0, v[30:31]
	v_lshlrev_b64 v[6:7], 11, v[2:3]
	v_ashrrev_i32_e32 v11, 31, v10
	v_add_u32_e32 v14, 0x80, v2
	s_and_b32 s17, s0, 0xfffffc00
	v_lshl_add_u64 v[8:9], v[4:5], 0, v[6:7]
	v_lshlrev_b64 v[10:11], 11, v[10:11]
	v_ashrrev_i32_e32 v15, 31, v14
	v_add_u32_e32 v2, 0xc0, v2
	v_add_u32_e32 v18, s11, v18
	s_mov_b32 m0, s17
	v_lshl_add_u64 v[12:13], v[4:5], 0, v[10:11]
	v_lshlrev_b64 v[14:15], 11, v[14:15]
	v_ashrrev_i32_e32 v3, 31, v2
	v_ashrrev_i32_e32 v19, 31, v18
	global_load_lds_dwordx4 v[8:9], off
	s_add_i32 m0, s17, 0x1000
	v_lshl_add_u64 v[16:17], v[4:5], 0, v[14:15]
	v_lshlrev_b64 v[2:3], 11, v[2:3]
	v_lshlrev_b64 v[22:23], 11, v[18:19]
	v_add_u32_e32 v18, 64, v18
	global_load_lds_dwordx4 v[12:13], off
	s_add_i32 m0, s17, 0x2000
	v_lshl_add_u64 v[4:5], v[4:5], 0, v[2:3]
	v_lshl_add_u64 v[20:21], s[52:53], 0, v[0:1]
	v_lshl_add_u64 v[20:21], v[20:21], 0, v[30:31]
	v_ashrrev_i32_e32 v19, 31, v18
	global_load_lds_dwordx4 v[16:17], off
	s_add_i32 m0, s17, 0x3000
	v_lshl_add_u64 v[24:25], v[20:21], 0, v[22:23]
	v_lshlrev_b64 v[18:19], 11, v[18:19]
	global_load_lds_dwordx4 v[4:5], off
	s_add_i32 m0, s17, 0x4000
	v_lshl_add_u64 v[20:21], v[20:21], 0, v[18:19]
	global_load_lds_dwordx4 v[24:25], off
	s_add_i32 m0, s17, 0x5000
	v_lshl_add_u64 v[8:9], v[8:9], 0, 64
	v_lshl_add_u64 v[8:9], v[8:9], 0, 64
	global_load_lds_dwordx4 v[20:21], off
	s_add_i32 m0, s17, 0x6000
	v_lshl_add_u64 v[4:5], v[4:5], 0, 64
	v_lshl_add_u64 v[4:5], v[4:5], 0, 64
	global_load_lds_dwordx4 v[8:9], off
	v_lshl_add_u64 v[8:9], v[12:13], 0, 64
	v_lshl_add_u64 v[8:9], v[8:9], 0, 64
	s_add_i32 m0, s17, 0x7000
	v_and_b32_e32 v0, 15, v26
	global_load_lds_dwordx4 v[8:9], off
	v_lshl_add_u64 v[8:9], v[16:17], 0, 64
	v_lshl_add_u64 v[8:9], v[8:9], 0, 64
	s_add_i32 m0, s17, 0x8000
	v_readlane_b32 s0, v253, 53
	global_load_lds_dwordx4 v[8:9], off
	s_add_i32 m0, s17, 0x9000
	v_readlane_b32 s1, v253, 54
	global_load_lds_dwordx4 v[4:5], off
	v_lshl_add_u64 v[4:5], v[24:25], 0, 64
	v_lshl_add_u64 v[4:5], v[4:5], 0, 64
	s_add_i32 m0, s17, 0xa000
	s_mov_b32 s13, 2
	global_load_lds_dwordx4 v[4:5], off
	v_lshl_add_u64 v[4:5], v[20:21], 0, 64
	v_lshl_add_u64 v[4:5], v[4:5], 0, 64
	s_add_i32 m0, s17, 0xb000
	s_mov_b32 s15, 0
	global_load_lds_dwordx4 v[4:5], off
	v_lshrrev_b32_e32 v5, 2, v26
	v_sub_u32_e32 v5, 0, v5
	v_xor_b32_e32 v5, v142, v5
	v_lshlrev_b32_e32 v5, 4, v5
	v_or_b32_e32 v4, s16, v0
	v_and_b32_e32 v5, 48, v5
	v_lshl_or_b32 v143, v4, 6, v5
	v_or_b32_e32 v4, s12, v0
	v_lshlrev_b32_e32 v4, 6, v4
	v_or3_b32 v144, v5, v4, s77
	v_bitop3_b32 v4, v26, 3, v27 bitop3:0x48
	v_lshlrev_b32_e32 v4, 4, v4
	v_or_b32_e32 v18, v18, v4
	v_or_b32_e32 v22, v22, v4
	v_lshl_add_u64 v[130:131], s[0:1], 0, v[18:19]
	v_lshl_add_u64 v[132:133], s[0:1], 0, v[22:23]
	v_readlane_b32 s0, v253, 55
	v_or_b32_e32 v2, v2, v4
	v_readlane_b32 s1, v253, 56
	v_or_b32_e32 v14, v14, v4
;   DI bf16* K() const { return (bf16*)(p.ws + WS_K); }
; template <class AP, class BP, class Epi>
; DI void mfma_gemm_big_tile(const AP& aptr, const BP& bptr, int m0, int n0, int K, const Epi& epi, bf16* lds) {
;     ...
;   const bf16* ap[4]; const bf16* bp[2];
; #pragma unroll
;   for (int i = 0; i < 4; ++i) ap[i] = aptr(m0 + lrow + 64 * i) + lcol;
; #pragma unroll
;   for (int i = 0; i < 2; ++i) bp[i] = bptr(n0 + lrow + 64 * i) + lcol;
;   f32x4 acc[8][4];
; #pragma unroll
;   for (int i = 0; i < 8; ++i)
; #pragma unroll
;     for (int j = 0; j < 4; ++j) acc[i][j] = f32x4{0.f, 0.f, 0.f, 0.f};
;   const int nk = K >> 5;
;     ...
;   BG_ISSUE(0, 0);
;   BG_ISSUE(1, 1);
;   asm volatile("s_waitcnt vmcnt(6)\n\ts_barrier" ::: "memory");
	v_or_b32_e32 v10, v10, v4
	v_lshl_add_u64 v[134:135], s[0:1], 0, v[2:3]
	v_or_b32_e32 v6, v6, v4
	v_mov_b32_e32 v2, 0
	v_lshl_add_u64 v[136:137], s[0:1], 0, v[14:15]
	v_lshl_add_u64 v[138:139], s[0:1], 0, v[10:11]
	v_lshl_add_u64 v[140:141], s[0:1], 0, v[6:7]
	v_lshl_add_u64 v[30:31], v[30:31], 0, 64
	v_lshl_add_u64 v[30:31], v[30:31], 0, 64
	v_lshl_add_u64 v[130:131], v[130:131], 0, v[30:31]
	v_lshl_add_u64 v[132:133], v[132:133], 0, v[30:31]
	v_lshl_add_u64 v[134:135], v[134:135], 0, v[30:31]
	v_lshl_add_u64 v[136:137], v[136:137], 0, v[30:31]
	v_lshl_add_u64 v[138:139], v[138:139], 0, v[30:31]
	v_lshl_add_u64 v[140:141], v[140:141], 0, v[30:31]
	s_mov_b64 s[0:1], 0
	s_mov_b32 s18, 0
	v_mov_b32_e32 v3, v2
	v_mov_b32_e32 v4, v2
	v_mov_b32_e32 v5, v2
	v_mov_b32_e32 v6, v2
	v_mov_b32_e32 v7, v2
	v_mov_b32_e32 v8, v2
	v_mov_b32_e32 v9, v2
	v_mov_b32_e32 v10, v2
	v_mov_b32_e32 v11, v2
	v_mov_b32_e32 v12, v2
	v_mov_b32_e32 v13, v2
	v_mov_b32_e32 v14, v2
	v_mov_b32_e32 v15, v2
	v_mov_b32_e32 v16, v2
	v_mov_b32_e32 v17, v2
	v_mov_b32_e32 v18, v2
	v_mov_b32_e32 v19, v2
	v_mov_b32_e32 v20, v2
	v_mov_b32_e32 v21, v2
	v_mov_b32_e32 v22, v2
	v_mov_b32_e32 v23, v2
	v_mov_b32_e32 v24, v2
	v_mov_b32_e32 v25, v2
	v_mov_b32_e32 v26, v2
	v_mov_b32_e32 v27, v2
	v_mov_b32_e32 v28, v2
	v_mov_b32_e32 v29, v2
	v_mov_b32_e32 v30, v2
	v_mov_b32_e32 v31, v2
	v_mov_b32_e32 v32, v2
	v_mov_b32_e32 v33, v2
	v_mov_b32_e32 v34, v2
	v_mov_b32_e32 v35, v2
	v_mov_b32_e32 v36, v2
	v_mov_b32_e32 v37, v2
	v_mov_b32_e32 v38, v2
	v_mov_b32_e32 v39, v2
	v_mov_b32_e32 v40, v2
	v_mov_b32_e32 v41, v2
	v_mov_b32_e32 v42, v2
	v_mov_b32_e32 v43, v2
	v_mov_b32_e32 v44, v2
	v_mov_b32_e32 v45, v2
	v_mov_b32_e32 v46, v2
	v_mov_b32_e32 v47, v2
	v_mov_b32_e32 v48, v2
	v_mov_b32_e32 v49, v2
	v_mov_b32_e32 v50, v2
	v_mov_b32_e32 v51, v2
	v_mov_b32_e32 v52, v2
	v_mov_b32_e32 v53, v2
	v_mov_b32_e32 v54, v2
	v_mov_b32_e32 v55, v2
	v_mov_b32_e32 v56, v2
	v_mov_b32_e32 v57, v2
	v_mov_b32_e32 v58, v2
	v_mov_b32_e32 v59, v2
	v_mov_b32_e32 v60, v2
	v_mov_b32_e32 v61, v2
	v_mov_b32_e32 v62, v2
	v_mov_b32_e32 v63, v2
	v_mov_b32_e32 v64, v2
	v_mov_b32_e32 v65, v2
	v_mov_b32_e32 v66, v2
	v_mov_b32_e32 v67, v2
	v_mov_b32_e32 v68, v2
	v_mov_b32_e32 v69, v2
	v_mov_b32_e32 v70, v2
	v_mov_b32_e32 v71, v2
	v_mov_b32_e32 v72, v2
	v_mov_b32_e32 v73, v2
	v_mov_b32_e32 v74, v2
	v_mov_b32_e32 v75, v2
	v_mov_b32_e32 v76, v2
	v_mov_b32_e32 v77, v2
	v_mov_b32_e32 v78, v2
	v_mov_b32_e32 v79, v2
	v_mov_b32_e32 v80, v2
	v_mov_b32_e32 v81, v2
	v_mov_b32_e32 v82, v2
	v_mov_b32_e32 v83, v2
	v_mov_b32_e32 v84, v2
	v_mov_b32_e32 v85, v2
	v_mov_b32_e32 v86, v2
	v_mov_b32_e32 v87, v2
	v_mov_b32_e32 v88, v2
	v_mov_b32_e32 v89, v2
	v_mov_b32_e32 v90, v2
	v_mov_b32_e32 v91, v2
	v_mov_b32_e32 v92, v2
	v_mov_b32_e32 v93, v2
	v_mov_b32_e32 v94, v2
	v_mov_b32_e32 v95, v2
	v_mov_b32_e32 v96, v2
	v_mov_b32_e32 v97, v2
	v_mov_b32_e32 v98, v2
	v_mov_b32_e32 v99, v2
	v_mov_b32_e32 v100, v2
	v_mov_b32_e32 v101, v2
	v_mov_b32_e32 v102, v2
	v_mov_b32_e32 v103, v2
	v_mov_b32_e32 v104, v2
	v_mov_b32_e32 v105, v2
	v_mov_b32_e32 v106, v2
	v_mov_b32_e32 v107, v2
	v_mov_b32_e32 v108, v2
	v_mov_b32_e32 v109, v2
	v_mov_b32_e32 v110, v2
	v_mov_b32_e32 v111, v2
	v_mov_b32_e32 v112, v2
	v_mov_b32_e32 v113, v2
	v_mov_b32_e32 v114, v2
	v_mov_b32_e32 v115, v2
	v_mov_b32_e32 v116, v2
	v_mov_b32_e32 v117, v2
	v_mov_b32_e32 v118, v2
	v_mov_b32_e32 v119, v2
	v_mov_b32_e32 v120, v2
	v_mov_b32_e32 v121, v2
	v_mov_b32_e32 v122, v2
	v_mov_b32_e32 v123, v2
	v_mov_b32_e32 v124, v2
	v_mov_b32_e32 v125, v2
	v_mov_b32_e32 v126, v2
	v_mov_b32_e32 v127, v2
	v_mov_b32_e32 v128, v2
	v_mov_b32_e32 v129, v2
	s_waitcnt vmcnt(6)
	s_barrier
	s_branch .LBB0_510

; DI int otid() { int t = threadIdx.x; asm volatile("" : "+v"(t)); return t; }
;   DI bf16* K() const { return (bf16*)(p.ws + WS_K); }
; template <class AP, class BP, class Epi>
; DI void mfma_gemm_big_tile(const AP& aptr, const BP& bptr, int m0, int n0, int K, const Epi& epi, bf16* lds) {
;   const int tid = otid(), lane = tid & 63, wave = __builtin_amdgcn_readfirstlane(tid >> 6);
;   const int wm = (wave >> 1) * 128, wn = (wave & 1) * 64;
;   const int l16 = lane & 15, lq = lane >> 4;
;   const int lrow = tid >> 2, lcol = ((tid & 3) ^ ((-(tid >> 4)) & 3)) * 8;
;   const bf16* ap[4]; const bf16* bp[2];
; #pragma unroll
;   for (int i = 0; i < 4; ++i) ap[i] = aptr(m0 + lrow + 64 * i) + lcol;
; #pragma unroll
;   for (int i = 0; i < 2; ++i) bp[i] = bptr(n0 + lrow + 64 * i) + lcol;
;   f32x4 acc[8][4];
; #pragma unroll
;   for (int i = 0; i < 8; ++i)
; #pragma unroll
;     for (int j = 0; j < 4; ++j) acc[i][j] = f32x4{0.f, 0.f, 0.f, 0.f};
;   const int nk = K >> 5;
;     ...
;   BG_ISSUE(0, 0);
;   BG_ISSUE(1, 1);
;   asm volatile("s_waitcnt vmcnt(6)\n\ts_barrier" ::: "memory");
;   const unsigned lbase = (unsigned)(size_t)lds;
;   const unsigned a_off = (unsigned)(((wm + l16) * 32 + (lq ^ ((-(l16 >> 2)) & 3)) * 8) * 2);
;   const unsigned b_off = (unsigned)((256 * 32 + (wn + l16) * 32 + (lq ^ ((-(l16 >> 2)) & 3)) * 8) * 2);
.LBB0_1105:
	s_add_i32 s0, s13, s74
	s_ashr_i32 s1, s0, 31
	s_lshr_b32 s1, s1, 29
	v_mov_b32_e32 v26, v172
	s_add_i32 s1, s0, s1
	s_lshl_b32 s8, s1, 5
	v_lshrrev_b32_e32 v142, 4, v26
	s_and_b32 s1, s1, 0x1fffff8
	v_sub_u32_e32 v27, 0, v142
	s_and_b32 s14, s8, 0xffffff00
	s_sub_i32 s0, s0, s1
	v_ashrrev_i32_e32 v18, 2, v26
	v_xor_b32_e32 v0, v26, v27
	s_lshl_b32 s15, s0, 7
	v_readfirstlane_b32 s0, v26
	v_add_u32_e32 v2, s14, v18
	v_lshlrev_b32_e32 v0, 4, v0
	s_and_b32 s16, s0, 64
	v_and_b32_e32 v0, 48, v0
	v_ashrrev_i32_e32 v3, 31, v2
	v_add_u32_e32 v10, 64, v2
	s_and_b32 s19, s0, 0xffffff80
	s_lshl_b32 s0, s0, 4
	v_lshl_add_u64 v[4:5], s[60:61], 0, v[0:1]
	v_bfe_u32 v30, v26, 2, 1
	v_mul_i32_i24_e32 v30, 0xfffff840, v30
	v_ashrrev_i32_e32 v31, 31, v30
	v_lshl_add_u64 v[4:5], v[4:5], 0, v[30:31]
	v_lshlrev_b64 v[6:7], 11, v[2:3]
	v_ashrrev_i32_e32 v11, 31, v10
	v_add_u32_e32 v14, 0x80, v2
	s_and_b32 s20, s0, 0xfffffc00
	v_lshl_add_u64 v[8:9], v[4:5], 0, v[6:7]
	v_lshlrev_b64 v[10:11], 11, v[10:11]
	v_ashrrev_i32_e32 v15, 31, v14
	v_add_u32_e32 v2, 0xc0, v2
	v_add_u32_e32 v18, s15, v18
	s_mov_b32 m0, s20
	v_lshl_add_u64 v[12:13], v[4:5], 0, v[10:11]
	v_lshlrev_b64 v[14:15], 11, v[14:15]
	v_ashrrev_i32_e32 v3, 31, v2
	v_ashrrev_i32_e32 v19, 31, v18
	global_load_lds_dwordx4 v[8:9], off
	s_add_i32 m0, s20, 0x1000
	v_lshl_add_u64 v[16:17], v[4:5], 0, v[14:15]
	v_lshlrev_b64 v[2:3], 11, v[2:3]
	v_lshlrev_b64 v[22:23], 11, v[18:19]
	v_add_u32_e32 v18, 64, v18
	global_load_lds_dwordx4 v[12:13], off
	s_add_i32 m0, s20, 0x2000
	v_lshl_add_u64 v[4:5], v[4:5], 0, v[2:3]
	v_lshl_add_u64 v[20:21], s[44:45], 0, v[0:1]
	v_ashrrev_i32_e32 v19, 31, v18
	global_load_lds_dwordx4 v[16:17], off
	s_add_i32 m0, s20, 0x3000
	v_lshl_add_u64 v[24:25], v[20:21], 0, v[22:23]
	v_lshlrev_b64 v[18:19], 11, v[18:19]
	global_load_lds_dwordx4 v[4:5], off
	s_add_i32 m0, s20, 0x4000
	v_lshl_add_u64 v[20:21], v[20:21], 0, v[18:19]
	global_load_lds_dwordx4 v[24:25], off
	s_add_i32 m0, s20, 0x5000
	v_lshl_add_u64 v[8:9], v[8:9], 0, 64
	v_lshl_add_u64 v[8:9], v[8:9], 0, 64
	global_load_lds_dwordx4 v[20:21], off
	s_add_i32 m0, s20, 0x6000
	v_lshl_add_u64 v[4:5], v[4:5], 0, 64
	v_lshl_add_u64 v[4:5], v[4:5], 0, 64
	global_load_lds_dwordx4 v[8:9], off
	v_lshl_add_u64 v[8:9], v[12:13], 0, 64
	v_lshl_add_u64 v[8:9], v[8:9], 0, 64
	s_add_i32 m0, s20, 0x7000
	v_and_b32_e32 v0, 15, v26
	global_load_lds_dwordx4 v[8:9], off
	v_lshl_add_u64 v[8:9], v[16:17], 0, 64
	v_lshl_add_u64 v[8:9], v[8:9], 0, 64
	s_add_i32 m0, s20, 0x8000
	v_readlane_b32 s0, v254, 0
	global_load_lds_dwordx4 v[8:9], off
	s_add_i32 m0, s20, 0x9000
	v_readlane_b32 s1, v254, 1
	global_load_lds_dwordx4 v[4:5], off
	v_lshl_add_u64 v[4:5], v[24:25], 0, 64
	s_add_i32 m0, s20, 0xa000
	s_mov_b32 s17, 2
	global_load_lds_dwordx4 v[4:5], off
	v_lshl_add_u64 v[4:5], v[20:21], 0, 64
	s_add_i32 m0, s20, 0xb000
	s_mov_b32 s18, 0
	global_load_lds_dwordx4 v[4:5], off
	v_lshrrev_b32_e32 v5, 2, v26
	v_sub_u32_e32 v5, 0, v5
	v_xor_b32_e32 v5, v142, v5
	v_lshlrev_b32_e32 v5, 4, v5
	v_or_b32_e32 v4, s19, v0
	v_and_b32_e32 v5, 48, v5
	v_lshl_or_b32 v143, v4, 6, v5
	v_or_b32_e32 v4, s16, v0
	v_lshlrev_b32_e32 v4, 6, v4
	v_or3_b32 v144, v4, v5, s77
	v_bitop3_b32 v4, v26, 3, v27 bitop3:0x48
	v_lshlrev_b32_e32 v4, 4, v4
	v_or_b32_e32 v18, v18, v4
	v_or_b32_e32 v22, v22, v4
	v_lshl_add_u64 v[130:131], s[0:1], 0, v[18:19]
	v_lshl_add_u64 v[132:133], s[0:1], 0, v[22:23]
	v_readlane_b32 s0, v253, 55
	v_or_b32_e32 v2, v2, v4
	v_readlane_b32 s1, v253, 56
	v_or_b32_e32 v14, v14, v4
	v_or_b32_e32 v10, v10, v4
;   DI bf16* K() const { return (bf16*)(p.ws + WS_K); }
; template <class AP, class BP, class Epi>
; DI void mfma_gemm_big_tile(const AP& aptr, const BP& bptr, int m0, int n0, int K, const Epi& epi, bf16* lds) {
;     ...
;   const bf16* ap[4]; const bf16* bp[2];
; #pragma unroll
;   for (int i = 0; i < 4; ++i) ap[i] = aptr(m0 + lrow + 64 * i) + lcol;
; #pragma unroll
;   for (int i = 0; i < 2; ++i) bp[i] = bptr(n0 + lrow + 64 * i) + lcol;
;   f32x4 acc[8][4];
; #pragma unroll
;   for (int i = 0; i < 8; ++i)
; #pragma unroll
;     for (int j = 0; j < 4; ++j) acc[i][j] = f32x4{0.f, 0.f, 0.f, 0.f};
;   const int nk = K >> 5;
;     ...
;   BG_ISSUE(0, 0);
;   BG_ISSUE(1, 1);
;   asm volatile("s_waitcnt vmcnt(6)\n\ts_barrier" ::: "memory");
	v_lshl_add_u64 v[134:135], s[0:1], 0, v[2:3]
	v_or_b32_e32 v6, v6, v4
	v_mov_b32_e32 v2, 0
	v_lshl_add_u64 v[136:137], s[0:1], 0, v[14:15]
	v_lshl_add_u64 v[138:139], s[0:1], 0, v[10:11]
	v_lshl_add_u64 v[140:141], s[0:1], 0, v[6:7]
	v_lshl_add_u64 v[30:31], v[30:31], 0, 64
	v_lshl_add_u64 v[30:31], v[30:31], 0, 64
	v_lshl_add_u64 v[134:135], v[134:135], 0, v[30:31]
	v_lshl_add_u64 v[136:137], v[136:137], 0, v[30:31]
	v_lshl_add_u64 v[138:139], v[138:139], 0, v[30:31]
	v_lshl_add_u64 v[140:141], v[140:141], 0, v[30:31]
	s_mov_b64 s[0:1], 0
	s_mov_b32 s21, 0
	v_mov_b32_e32 v3, v2
	v_mov_b32_e32 v4, v2
	v_mov_b32_e32 v5, v2
	v_mov_b32_e32 v6, v2
	v_mov_b32_e32 v7, v2
	v_mov_b32_e32 v8, v2
	v_mov_b32_e32 v9, v2
	v_mov_b32_e32 v10, v2
	v_mov_b32_e32 v11, v2
	v_mov_b32_e32 v12, v2
	v_mov_b32_e32 v13, v2
	v_mov_b32_e32 v14, v2
	v_mov_b32_e32 v15, v2
	v_mov_b32_e32 v16, v2
	v_mov_b32_e32 v17, v2
	v_mov_b32_e32 v18, v2
	v_mov_b32_e32 v19, v2
	v_mov_b32_e32 v20, v2
	v_mov_b32_e32 v21, v2
	v_mov_b32_e32 v22, v2
	v_mov_b32_e32 v23, v2
	v_mov_b32_e32 v24, v2
	v_mov_b32_e32 v25, v2
	v_mov_b32_e32 v26, v2
	v_mov_b32_e32 v27, v2
	v_mov_b32_e32 v28, v2
	v_mov_b32_e32 v29, v2
	v_mov_b32_e32 v30, v2
	v_mov_b32_e32 v31, v2
	v_mov_b32_e32 v32, v2
	v_mov_b32_e32 v33, v2
	v_mov_b32_e32 v34, v2
	v_mov_b32_e32 v35, v2
	v_mov_b32_e32 v36, v2
	v_mov_b32_e32 v37, v2
	v_mov_b32_e32 v38, v2
	v_mov_b32_e32 v39, v2
	v_mov_b32_e32 v40, v2
	v_mov_b32_e32 v41, v2
	v_mov_b32_e32 v42, v2
	v_mov_b32_e32 v43, v2
	v_mov_b32_e32 v44, v2
	v_mov_b32_e32 v45, v2
	v_mov_b32_e32 v46, v2
	v_mov_b32_e32 v47, v2
	v_mov_b32_e32 v48, v2
	v_mov_b32_e32 v49, v2
	v_mov_b32_e32 v50, v2
	v_mov_b32_e32 v51, v2
	v_mov_b32_e32 v52, v2
	v_mov_b32_e32 v53, v2
	v_mov_b32_e32 v54, v2
	v_mov_b32_e32 v55, v2
	v_mov_b32_e32 v56, v2
	v_mov_b32_e32 v57, v2
	v_mov_b32_e32 v58, v2
	v_mov_b32_e32 v59, v2
	v_mov_b32_e32 v60, v2
	v_mov_b32_e32 v61, v2
	v_mov_b32_e32 v62, v2
	v_mov_b32_e32 v63, v2
	v_mov_b32_e32 v64, v2
	v_mov_b32_e32 v65, v2
	v_mov_b32_e32 v66, v2
	v_mov_b32_e32 v67, v2
	v_mov_b32_e32 v68, v2
	v_mov_b32_e32 v69, v2
	v_mov_b32_e32 v70, v2
	v_mov_b32_e32 v71, v2
	v_mov_b32_e32 v72, v2
	v_mov_b32_e32 v73, v2
	v_mov_b32_e32 v74, v2
	v_mov_b32_e32 v75, v2
	v_mov_b32_e32 v76, v2
	v_mov_b32_e32 v77, v2
	v_mov_b32_e32 v78, v2
	v_mov_b32_e32 v79, v2
	v_mov_b32_e32 v80, v2
	v_mov_b32_e32 v81, v2
	v_mov_b32_e32 v82, v2
	v_mov_b32_e32 v83, v2
	v_mov_b32_e32 v84, v2
	v_mov_b32_e32 v85, v2
	v_mov_b32_e32 v86, v2
	v_mov_b32_e32 v87, v2
	v_mov_b32_e32 v88, v2
	v_mov_b32_e32 v89, v2
	v_mov_b32_e32 v90, v2
	v_mov_b32_e32 v91, v2
	v_mov_b32_e32 v92, v2
	v_mov_b32_e32 v93, v2
	v_mov_b32_e32 v94, v2
	v_mov_b32_e32 v95, v2
	v_mov_b32_e32 v96, v2
	v_mov_b32_e32 v97, v2
	v_mov_b32_e32 v98, v2
	v_mov_b32_e32 v99, v2
	v_mov_b32_e32 v100, v2
	v_mov_b32_e32 v101, v2
	v_mov_b32_e32 v102, v2
	v_mov_b32_e32 v103, v2
	v_mov_b32_e32 v104, v2
	v_mov_b32_e32 v105, v2
	v_mov_b32_e32 v106, v2
	v_mov_b32_e32 v107, v2
	v_mov_b32_e32 v108, v2
	v_mov_b32_e32 v109, v2
	v_mov_b32_e32 v110, v2
	v_mov_b32_e32 v111, v2
	v_mov_b32_e32 v112, v2
	v_mov_b32_e32 v113, v2
	v_mov_b32_e32 v114, v2
	v_mov_b32_e32 v115, v2
	v_mov_b32_e32 v116, v2
	v_mov_b32_e32 v117, v2
	v_mov_b32_e32 v118, v2
	v_mov_b32_e32 v119, v2
	v_mov_b32_e32 v120, v2
	v_mov_b32_e32 v121, v2
	v_mov_b32_e32 v122, v2
	v_mov_b32_e32 v123, v2
	v_mov_b32_e32 v124, v2
	v_mov_b32_e32 v125, v2
	v_mov_b32_e32 v126, v2
	v_mov_b32_e32 v127, v2
	v_mov_b32_e32 v128, v2
	v_mov_b32_e32 v129, v2
	s_waitcnt vmcnt(6)
	s_barrier
	s_branch .LBB0_1107
